# non-temporal (nt) hint on the residual-source loads of the G2/DN residual epilogue
# speedup vs baseline: 1.0063x; 1.0063x over previous
;     __device__ __forceinline__ void operator()(const f32x4 (&acc)[2][2][4][2], const Unit& u, int wr, int wc, int fr, int fq) const {
;         const float* src; float* dst; int b;
;         if (u.pm < 128) { src = src_lat + (size_t)u.pm * BM * 1024; dst = dst_lat + (size_t)u.pm * BM * 1024; b = u.pm >> 5; }
;         else { src = src_ctx + (size_t)(u.pm - 128) * BM * 1024; dst = dst_ctx + (size_t)(u.pm - 128) * BM * 1024; b = 4; }
;         const float* g = gate + b * 6144;
;         const int col0 = u.pn * BM + wc * 32 + 4 * fq;
; #pragma unroll
;         for (int bj = 0; bj < 2; ++bj)
; #pragma unroll
;             for (int n = 0; n < 2; ++n) { const f32x4 gv = *(const f32x4*)(g + col0 + bj * HALF + n * 16);
; #pragma unroll
;                 for (int ai = 0; ai < 2; ++ai)
; #pragma unroll
;                     for (int m = 0; m < 4; ++m) { const size_t off = (size_t)(ai * HALF + wr * 64 + m * 16 + fr) * 1024 + col0 + bj * HALF + n * 16;
;                         const f32x4 s = *(const f32x4*)(src + off); *(f32x4*)(dst + off) = s + gv * acc[ai][bj][m][n]; } }
.LBB0_549:
	s_lshl_b64 s[14:15], s[20:21], 2
	s_add_u32 s14, s35, s14
	s_addc_u32 s15, s36, s15
	s_add_u32 s20, s18, 0x80000
	s_addc_u32 s21, s19, 0
	s_add_u32 s22, s16, 0x80000
	s_addc_u32 s23, s17, 0
	v_mbcnt_lo_u32_b32 v186, -1, 0
	v_mbcnt_hi_u32_b32 v186, -1, v186
	v_lshrrev_b32_e32 v187, 10, v142
	v_and_b32_e32 v187, 64, v187
	v_and_b32_e32 v188, 0x60, v169
	v_mul_u32_u24_e32 v189, 0xc0, v187
	v_mul_u32_u24_e32 v192, 0x60, v188
	v_add_u32_e32 v189, v189, v192
	v_add_u32_e32 v189, 0x20000, v189
	v_and_b32_e32 v192, 15, v186
	v_lshrrev_b32_e32 v193, 4, v186
	v_mul_u32_u24_e32 v192, 0x90, v192
	v_lshl_add_u32 v192, v193, 4, v192
	v_add_u32_e32 v38, v189, v192
	v_lshrrev_b32_e32 v190, 3, v186
	v_and_b32_e32 v191, 7, v186
	v_mul_u32_u24_e32 v192, 0x90, v190
	v_lshl_add_u32 v192, v191, 4, v192
	v_add_u32_e32 v250, v189, v192
	v_add_u32_e32 v193, v187, v190
	v_lshlrev_b32_e32 v193, 12, v193
	v_lshl_or_b32 v193, v188, 2, v193
	v_lshl_or_b32 v193, v191, 4, v193
	v_lshl_or_b32 v166, s40, 10, v193
	v_and_b32_e32 v251, 0xfff, v166
	v_add_u32_e32 v167, 0x8000, v166
	v_add_u32_e32 v180, 0x10000, v166
	v_add_u32_e32 v181, 0x18000, v166
	v_add_u32_e32 v202, 0x20000, v166
	v_add_u32_e32 v203, 0x28000, v166
	v_add_u32_e32 v212, 0x30000, v166
	v_add_u32_e32 v213, 0x38000, v166
	global_load_dwordx4 v[138:141], v251, s[14:15]
	global_load_dwordx4 v[162:165], v251, s[14:15] offset:512
	global_load_dwordx4 v[172:175], v166, s[18:19] nt
	global_load_dwordx4 v[176:179], v166, s[18:19] offset:512 nt
	global_load_dwordx4 v[186:189], v167, s[18:19] nt
	global_load_dwordx4 v[190:193], v167, s[18:19] offset:512 nt
	global_load_dwordx4 v[194:197], v180, s[18:19] nt
	global_load_dwordx4 v[198:201], v180, s[18:19] offset:512 nt
	global_load_dwordx4 v[208:211], v181, s[18:19] nt
	global_load_dwordx4 v[218:221], v181, s[18:19] offset:512 nt
	global_load_dwordx4 v[226:229], v202, s[18:19] nt
	global_load_dwordx4 v[230:233], v202, s[18:19] offset:512 nt
	global_load_dwordx4 v[234:237], v203, s[18:19] nt
	global_load_dwordx4 v[238:241], v203, s[18:19] offset:512 nt
	global_load_dwordx4 v[242:245], v212, s[18:19] nt
	global_load_dwordx4 v[246:249], v212, s[18:19] offset:512 nt
	ds_write_b128 v38, v[134:137]
	ds_write_b128 v38, v[106:109] offset:64
	ds_read_b128 v[134:137], v250
	ds_read_b128 v[106:109], v250 offset:1152
	ds_write_b128 v38, v[82:85]
	ds_write_b128 v38, v[54:57] offset:64
	ds_read_b128 v[82:85], v250
	ds_read_b128 v[54:57], v250 offset:1152
	ds_write_b128 v38, v[130:133]
	ds_write_b128 v38, v[102:105] offset:64
	ds_read_b128 v[130:133], v250
	ds_read_b128 v[102:105], v250 offset:1152
	ds_write_b128 v38, v[74:77]
	ds_write_b128 v38, v[46:49] offset:64
	ds_read_b128 v[74:77], v250
	ds_read_b128 v[46:49], v250 offset:1152
	ds_write_b128 v38, v[126:129]
	ds_write_b128 v38, v[98:101] offset:64
	ds_read_b128 v[126:129], v250
	ds_read_b128 v[98:101], v250 offset:1152
	ds_write_b128 v38, v[66:69]
	ds_write_b128 v38, v[30:33] offset:64
	ds_read_b128 v[66:69], v250
	ds_read_b128 v[30:33], v250 offset:1152
	ds_write_b128 v38, v[122:125]
	ds_write_b128 v38, v[90:93] offset:64
	ds_read_b128 v[122:125], v250
	ds_read_b128 v[90:93], v250 offset:1152
	ds_write_b128 v38, v[58:61]
	ds_write_b128 v38, v[22:25] offset:64
	ds_read_b128 v[58:61], v250
	ds_read_b128 v[22:25], v250 offset:1152
	ds_write_b128 v38, v[118:121]
	ds_write_b128 v38, v[86:89] offset:64
	ds_read_b128 v[118:121], v250
	ds_read_b128 v[86:89], v250 offset:1152
	ds_write_b128 v38, v[50:53]
	ds_write_b128 v38, v[14:17] offset:64
	ds_read_b128 v[50:53], v250
	ds_read_b128 v[14:17], v250 offset:1152
	ds_write_b128 v38, v[114:117]
	ds_write_b128 v38, v[78:81] offset:64
	ds_read_b128 v[114:117], v250
	ds_read_b128 v[78:81], v250 offset:1152
	ds_write_b128 v38, v[42:45]
	ds_write_b128 v38, v[10:13] offset:64
	ds_read_b128 v[42:45], v250
	ds_read_b128 v[10:13], v250 offset:1152
	ds_write_b128 v38, v[110:113]
	ds_write_b128 v38, v[70:73] offset:64
	ds_read_b128 v[110:113], v250
	ds_read_b128 v[70:73], v250 offset:1152
	ds_write_b128 v38, v[26:29]
	ds_write_b128 v38, v[6:9] offset:64
	ds_read_b128 v[26:29], v250
	ds_read_b128 v[6:9], v250 offset:1152
	ds_write_b128 v38, v[94:97]
	ds_write_b128 v38, v[62:65] offset:64
	ds_read_b128 v[94:97], v250
	ds_read_b128 v[62:65], v250 offset:1152
	ds_write_b128 v38, v[18:21]
	ds_write_b128 v38, v[2:5] offset:64
	ds_read_b128 v[18:21], v250
	ds_read_b128 v[2:5], v250 offset:1152
	s_waitcnt lgkmcnt(0)
	s_waitcnt vmcnt(13)
	v_pk_fma_f32 v[134:135], v[134:135], v[138:139], v[172:173]
	v_pk_fma_f32 v[136:137], v[136:137], v[140:141], v[174:175]
	global_store_dwordx4 v166, v[134:137], s[16:17] sc1
	global_load_dwordx4 v[172:175], v213, s[18:19] nt
	s_waitcnt vmcnt(14)
	v_pk_fma_f32 v[82:83], v[82:83], v[162:163], v[176:177]
	v_pk_fma_f32 v[84:85], v[84:85], v[164:165], v[178:179]
	global_store_dwordx4 v166, v[82:85], s[16:17] offset:512 sc1
	global_load_dwordx4 v[176:179], v213, s[18:19] offset:512 nt
	s_waitcnt vmcnt(15)
	v_pk_fma_f32 v[106:107], v[106:107], v[138:139], v[186:187]
	v_pk_fma_f32 v[108:109], v[108:109], v[140:141], v[188:189]
	global_store_dwordx4 v167, v[106:109], s[16:17] sc1
	global_load_dwordx4 v[186:189], v166, s[20:21] nt
	s_waitcnt vmcnt(16)
	v_pk_fma_f32 v[54:55], v[54:55], v[162:163], v[190:191]
	v_pk_fma_f32 v[56:57], v[56:57], v[164:165], v[192:193]
	global_store_dwordx4 v167, v[54:57], s[16:17] offset:512 sc1
	global_load_dwordx4 v[190:193], v166, s[20:21] offset:512 nt
	s_waitcnt vmcnt(17)
	v_pk_fma_f32 v[130:131], v[130:131], v[138:139], v[194:195]
	v_pk_fma_f32 v[132:133], v[132:133], v[140:141], v[196:197]
	global_store_dwordx4 v180, v[130:133], s[16:17] sc1
	global_load_dwordx4 v[194:197], v167, s[20:21] nt
	s_waitcnt vmcnt(18)
; #define PG8_BAR __builtin_amdgcn_s_barrier()
;     __device__ __forceinline__ void operator()(const f32x4 (&acc)[2][2][4][2], const Unit& u, int wr, int wc, int fr, int fq) const {
;     ...
;                     for (int m = 0; m < 4; ++m) { const size_t off = (size_t)(ai * HALF + wr * 64 + m * 16 + fr) * 1024 + col0 + bj * HALF + n * 16;
;                         const f32x4 s = *(const f32x4*)(src + off); *(f32x4*)(dst + off) = s + gv * acc[ai][bj][m][n]; } }
; template <class Epi, class Sched, bool ALIGN_EPI = false, bool SP2 = false>
; __device__ __forceinline__ void gemm_phase(PG8_LAS unsigned char* lds, const Gemm g, const Sched& S, const Epi& E) {
;     ...
;         cur = nxt; cA = nA; cB = nB; ++ui;
;         if constexpr (ALIGN_EPI) { if (wr == 1) PG8_BAR; }
	v_pk_fma_f32 v[74:75], v[74:75], v[162:163], v[198:199]
	v_pk_fma_f32 v[76:77], v[76:77], v[164:165], v[200:201]
	global_store_dwordx4 v180, v[74:77], s[16:17] offset:512 sc1
	global_load_dwordx4 v[198:201], v167, s[20:21] offset:512 nt
	s_waitcnt vmcnt(19)
	v_pk_fma_f32 v[102:103], v[102:103], v[138:139], v[208:209]
	v_pk_fma_f32 v[104:105], v[104:105], v[140:141], v[210:211]
	global_store_dwordx4 v181, v[102:105], s[16:17] sc1
	global_load_dwordx4 v[208:211], v180, s[20:21] nt
	s_waitcnt vmcnt(20)
	v_pk_fma_f32 v[46:47], v[46:47], v[162:163], v[218:219]
	v_pk_fma_f32 v[48:49], v[48:49], v[164:165], v[220:221]
	global_store_dwordx4 v181, v[46:49], s[16:17] offset:512 sc1
	global_load_dwordx4 v[218:221], v180, s[20:21] offset:512 nt
	s_waitcnt vmcnt(21)
	v_pk_fma_f32 v[126:127], v[126:127], v[138:139], v[226:227]
	v_pk_fma_f32 v[128:129], v[128:129], v[140:141], v[228:229]
	global_store_dwordx4 v202, v[126:129], s[16:17] sc1
	global_load_dwordx4 v[226:229], v181, s[20:21] nt
	s_waitcnt vmcnt(22)
	v_pk_fma_f32 v[66:67], v[66:67], v[162:163], v[230:231]
	v_pk_fma_f32 v[68:69], v[68:69], v[164:165], v[232:233]
	global_store_dwordx4 v202, v[66:69], s[16:17] offset:512 sc1
	global_load_dwordx4 v[230:233], v181, s[20:21] offset:512 nt
	s_waitcnt vmcnt(23)
	v_pk_fma_f32 v[98:99], v[98:99], v[138:139], v[234:235]
	v_pk_fma_f32 v[100:101], v[100:101], v[140:141], v[236:237]
	global_store_dwordx4 v203, v[98:101], s[16:17] sc1
	global_load_dwordx4 v[234:237], v202, s[20:21] nt
	s_waitcnt vmcnt(24)
	v_pk_fma_f32 v[30:31], v[30:31], v[162:163], v[238:239]
	v_pk_fma_f32 v[32:33], v[32:33], v[164:165], v[240:241]
	global_store_dwordx4 v203, v[30:33], s[16:17] offset:512 sc1
	global_load_dwordx4 v[238:241], v202, s[20:21] offset:512 nt
	s_waitcnt vmcnt(25)
	v_pk_fma_f32 v[122:123], v[122:123], v[138:139], v[242:243]
	v_pk_fma_f32 v[124:125], v[124:125], v[140:141], v[244:245]
	global_store_dwordx4 v212, v[122:125], s[16:17] sc1
	global_load_dwordx4 v[242:245], v203, s[20:21] nt
	s_waitcnt vmcnt(26)
	v_pk_fma_f32 v[58:59], v[58:59], v[162:163], v[246:247]
	v_pk_fma_f32 v[60:61], v[60:61], v[164:165], v[248:249]
	global_store_dwordx4 v212, v[58:61], s[16:17] offset:512 sc1
	global_load_dwordx4 v[246:249], v203, s[20:21] offset:512 nt
	s_waitcnt vmcnt(26)
	v_pk_fma_f32 v[90:91], v[90:91], v[138:139], v[172:173]
	v_pk_fma_f32 v[92:93], v[92:93], v[140:141], v[174:175]
	global_store_dwordx4 v213, v[90:93], s[16:17] sc1
	global_load_dwordx4 v[172:175], v212, s[20:21] nt
	s_waitcnt vmcnt(26)
	v_pk_fma_f32 v[22:23], v[22:23], v[162:163], v[176:177]
	v_pk_fma_f32 v[24:25], v[24:25], v[164:165], v[178:179]
	global_store_dwordx4 v213, v[22:25], s[16:17] offset:512 sc1
	global_load_dwordx4 v[176:179], v212, s[20:21] offset:512 nt
	s_waitcnt vmcnt(26)
	v_pk_fma_f32 v[118:119], v[118:119], v[138:139], v[186:187]
	v_pk_fma_f32 v[120:121], v[120:121], v[140:141], v[188:189]
	global_store_dwordx4 v166, v[118:121], s[22:23] sc1
	global_load_dwordx4 v[186:189], v213, s[20:21] nt
	s_waitcnt vmcnt(26)
	v_pk_fma_f32 v[50:51], v[50:51], v[162:163], v[190:191]
	v_pk_fma_f32 v[52:53], v[52:53], v[164:165], v[192:193]
	global_store_dwordx4 v166, v[50:53], s[22:23] offset:512 sc1
	global_load_dwordx4 v[190:193], v213, s[20:21] offset:512 nt
	s_waitcnt vmcnt(26)
	v_pk_fma_f32 v[86:87], v[86:87], v[138:139], v[194:195]
	v_pk_fma_f32 v[88:89], v[88:89], v[140:141], v[196:197]
	global_store_dwordx4 v167, v[86:89], s[22:23] sc1
	s_waitcnt vmcnt(25)
	v_pk_fma_f32 v[14:15], v[14:15], v[162:163], v[198:199]
	v_pk_fma_f32 v[16:17], v[16:17], v[164:165], v[200:201]
	global_store_dwordx4 v167, v[14:17], s[22:23] offset:512 sc1
	s_waitcnt vmcnt(24)
	v_pk_fma_f32 v[114:115], v[114:115], v[138:139], v[208:209]
	v_pk_fma_f32 v[116:117], v[116:117], v[140:141], v[210:211]
	global_store_dwordx4 v180, v[114:117], s[22:23] sc1
	s_waitcnt vmcnt(23)
	v_pk_fma_f32 v[42:43], v[42:43], v[162:163], v[218:219]
	v_pk_fma_f32 v[44:45], v[44:45], v[164:165], v[220:221]
	global_store_dwordx4 v180, v[42:45], s[22:23] offset:512 sc1
	s_waitcnt vmcnt(22)
	v_pk_fma_f32 v[78:79], v[78:79], v[138:139], v[226:227]
	v_pk_fma_f32 v[80:81], v[80:81], v[140:141], v[228:229]
	global_store_dwordx4 v181, v[78:81], s[22:23] sc1
	s_waitcnt vmcnt(21)
	v_pk_fma_f32 v[10:11], v[10:11], v[162:163], v[230:231]
	v_pk_fma_f32 v[12:13], v[12:13], v[164:165], v[232:233]
	global_store_dwordx4 v181, v[10:13], s[22:23] offset:512 sc1
	s_waitcnt vmcnt(20)
	v_pk_fma_f32 v[110:111], v[110:111], v[138:139], v[234:235]
	v_pk_fma_f32 v[112:113], v[112:113], v[140:141], v[236:237]
	global_store_dwordx4 v202, v[110:113], s[22:23] sc1
	s_waitcnt vmcnt(19)
	v_pk_fma_f32 v[26:27], v[26:27], v[162:163], v[238:239]
	v_pk_fma_f32 v[28:29], v[28:29], v[164:165], v[240:241]
	global_store_dwordx4 v202, v[26:29], s[22:23] offset:512 sc1
	s_waitcnt vmcnt(18)
	v_pk_fma_f32 v[70:71], v[70:71], v[138:139], v[242:243]
	v_pk_fma_f32 v[72:73], v[72:73], v[140:141], v[244:245]
	global_store_dwordx4 v203, v[70:73], s[22:23] sc1
	s_waitcnt vmcnt(17)
	v_pk_fma_f32 v[6:7], v[6:7], v[162:163], v[246:247]
	v_pk_fma_f32 v[8:9], v[8:9], v[164:165], v[248:249]
	global_store_dwordx4 v203, v[6:9], s[22:23] offset:512 sc1
	s_waitcnt vmcnt(16)
	v_pk_fma_f32 v[94:95], v[94:95], v[138:139], v[172:173]
	v_pk_fma_f32 v[96:97], v[96:97], v[140:141], v[174:175]
	global_store_dwordx4 v212, v[94:97], s[22:23] sc1
	s_waitcnt vmcnt(15)
	v_pk_fma_f32 v[18:19], v[18:19], v[162:163], v[176:177]
	v_pk_fma_f32 v[20:21], v[20:21], v[164:165], v[178:179]
	global_store_dwordx4 v212, v[18:21], s[22:23] offset:512 sc1
	s_waitcnt vmcnt(14)
	v_pk_fma_f32 v[62:63], v[62:63], v[138:139], v[186:187]
	v_pk_fma_f32 v[64:65], v[64:65], v[140:141], v[188:189]
	global_store_dwordx4 v213, v[62:65], s[22:23] sc1
	s_waitcnt vmcnt(13)
	v_pk_fma_f32 v[2:3], v[2:3], v[162:163], v[190:191]
	v_pk_fma_f32 v[4:5], v[4:5], v[164:165], v[192:193]
	global_store_dwordx4 v213, v[2:5], s[22:23] offset:512 sc1
	s_mov_b64 s[14:15], -1
	s_andn2_b64 vcc, exec, s[4:5]
	s_cbranch_vccnz .LBB0_534
	s_andn2_b64 vcc, exec, s[0:1]
	s_cbranch_vccnz .LBB0_533
	s_barrier
	s_branch .LBB0_533

;     __device__ __forceinline__ void operator()(const f32x4 (&acc)[2][2][4][2], const Unit& u, int wr, int wc, int fr, int fq) const {
;         const float* src; float* dst; int b;
;         if (u.pm < 128) { src = src_lat + (size_t)u.pm * BM * 1024; dst = dst_lat + (size_t)u.pm * BM * 1024; b = u.pm >> 5; }
;         else { src = src_ctx + (size_t)(u.pm - 128) * BM * 1024; dst = dst_ctx + (size_t)(u.pm - 128) * BM * 1024; b = 4; }
;         const float* g = gate + b * 6144;
;         const int col0 = u.pn * BM + wc * 32 + 4 * fq;
; #pragma unroll
;         for (int bj = 0; bj < 2; ++bj)
; #pragma unroll
;             for (int n = 0; n < 2; ++n) { const f32x4 gv = *(const f32x4*)(g + col0 + bj * HALF + n * 16);
; #pragma unroll
;                 for (int ai = 0; ai < 2; ++ai)
; #pragma unroll
;                     for (int m = 0; m < 4; ++m) { const size_t off = (size_t)(ai * HALF + wr * 64 + m * 16 + fr) * 1024 + col0 + bj * HALF + n * 16;
;                         const f32x4 s = *(const f32x4*)(src + off); *(f32x4*)(dst + off) = s + gv * acc[ai][bj][m][n]; } }
.LBB0_995:
	s_lshl_b64 s[10:11], s[16:17], 2
	s_add_u32 s10, s31, s10
	s_addc_u32 s11, s34, s11
	s_add_u32 s16, s14, 0x80000
	s_addc_u32 s17, s15, 0
	s_add_u32 s18, s12, 0x80000
	s_addc_u32 s19, s13, 0
	v_mbcnt_lo_u32_b32 v186, -1, 0
	v_mbcnt_hi_u32_b32 v186, -1, v186
	v_lshrrev_b32_e32 v187, 10, v142
	v_and_b32_e32 v187, 64, v187
	v_and_b32_e32 v188, 0x60, v169
	v_mul_u32_u24_e32 v189, 0xc0, v187
	v_mul_u32_u24_e32 v192, 0x60, v188
	v_add_u32_e32 v189, v189, v192
	v_add_u32_e32 v189, 0x20000, v189
	v_and_b32_e32 v192, 15, v186
	v_lshrrev_b32_e32 v193, 4, v186
	v_mul_u32_u24_e32 v192, 0x90, v192
	v_lshl_add_u32 v192, v193, 4, v192
	v_add_u32_e32 v38, v189, v192
	v_lshrrev_b32_e32 v190, 3, v186
	v_and_b32_e32 v191, 7, v186
	v_mul_u32_u24_e32 v192, 0x90, v190
	v_lshl_add_u32 v192, v191, 4, v192
	v_add_u32_e32 v250, v189, v192
	v_add_u32_e32 v193, v187, v190
	v_lshlrev_b32_e32 v193, 12, v193
	v_lshl_or_b32 v193, v188, 2, v193
	v_lshl_or_b32 v193, v191, 4, v193
	v_lshl_or_b32 v166, s40, 10, v193
	v_and_b32_e32 v251, 0xfff, v166
	v_add_u32_e32 v167, 0x8000, v166
	v_add_u32_e32 v180, 0x10000, v166
	v_add_u32_e32 v181, 0x18000, v166
	v_add_u32_e32 v202, 0x20000, v166
	v_add_u32_e32 v203, 0x28000, v166
	v_add_u32_e32 v212, 0x30000, v166
	v_add_u32_e32 v213, 0x38000, v166
	global_load_dwordx4 v[138:141], v251, s[10:11]
	global_load_dwordx4 v[162:165], v251, s[10:11] offset:512
	global_load_dwordx4 v[172:175], v166, s[14:15] nt
	global_load_dwordx4 v[176:179], v166, s[14:15] offset:512 nt
	global_load_dwordx4 v[186:189], v167, s[14:15] nt
	global_load_dwordx4 v[190:193], v167, s[14:15] offset:512 nt
	global_load_dwordx4 v[194:197], v180, s[14:15] nt
	global_load_dwordx4 v[198:201], v180, s[14:15] offset:512 nt
	global_load_dwordx4 v[208:211], v181, s[14:15] nt
	global_load_dwordx4 v[218:221], v181, s[14:15] offset:512 nt
	global_load_dwordx4 v[226:229], v202, s[14:15] nt
	global_load_dwordx4 v[230:233], v202, s[14:15] offset:512 nt
	global_load_dwordx4 v[234:237], v203, s[14:15] nt
	global_load_dwordx4 v[238:241], v203, s[14:15] offset:512 nt
	global_load_dwordx4 v[242:245], v212, s[14:15] nt
	global_load_dwordx4 v[246:249], v212, s[14:15] offset:512 nt
	ds_write_b128 v38, v[134:137]
	ds_write_b128 v38, v[106:109] offset:64
	ds_read_b128 v[134:137], v250
	ds_read_b128 v[106:109], v250 offset:1152
	ds_write_b128 v38, v[82:85]
	ds_write_b128 v38, v[54:57] offset:64
	ds_read_b128 v[82:85], v250
	ds_read_b128 v[54:57], v250 offset:1152
	ds_write_b128 v38, v[130:133]
	ds_write_b128 v38, v[102:105] offset:64
	ds_read_b128 v[130:133], v250
	ds_read_b128 v[102:105], v250 offset:1152
	ds_write_b128 v38, v[74:77]
	ds_write_b128 v38, v[46:49] offset:64
	ds_read_b128 v[74:77], v250
	ds_read_b128 v[46:49], v250 offset:1152
	ds_write_b128 v38, v[126:129]
	ds_write_b128 v38, v[98:101] offset:64
	ds_read_b128 v[126:129], v250
	ds_read_b128 v[98:101], v250 offset:1152
	ds_write_b128 v38, v[66:69]
	ds_write_b128 v38, v[30:33] offset:64
	ds_read_b128 v[66:69], v250
	ds_read_b128 v[30:33], v250 offset:1152
	ds_write_b128 v38, v[122:125]
	ds_write_b128 v38, v[90:93] offset:64
	ds_read_b128 v[122:125], v250
	ds_read_b128 v[90:93], v250 offset:1152
	ds_write_b128 v38, v[58:61]
	ds_write_b128 v38, v[22:25] offset:64
	ds_read_b128 v[58:61], v250
	ds_read_b128 v[22:25], v250 offset:1152
	ds_write_b128 v38, v[118:121]
	ds_write_b128 v38, v[86:89] offset:64
	ds_read_b128 v[118:121], v250
	ds_read_b128 v[86:89], v250 offset:1152
	ds_write_b128 v38, v[50:53]
	ds_write_b128 v38, v[14:17] offset:64
	ds_read_b128 v[50:53], v250
	ds_read_b128 v[14:17], v250 offset:1152
	ds_write_b128 v38, v[114:117]
	ds_write_b128 v38, v[78:81] offset:64
	ds_read_b128 v[114:117], v250
	ds_read_b128 v[78:81], v250 offset:1152
	ds_write_b128 v38, v[42:45]
	ds_write_b128 v38, v[10:13] offset:64
	ds_read_b128 v[42:45], v250
	ds_read_b128 v[10:13], v250 offset:1152
	ds_write_b128 v38, v[110:113]
	ds_write_b128 v38, v[70:73] offset:64
	ds_read_b128 v[110:113], v250
	ds_read_b128 v[70:73], v250 offset:1152
	ds_write_b128 v38, v[26:29]
	ds_write_b128 v38, v[6:9] offset:64
	ds_read_b128 v[26:29], v250
	ds_read_b128 v[6:9], v250 offset:1152
	ds_write_b128 v38, v[94:97]
	ds_write_b128 v38, v[62:65] offset:64
	ds_read_b128 v[94:97], v250
	ds_read_b128 v[62:65], v250 offset:1152
	ds_write_b128 v38, v[18:21]
	ds_write_b128 v38, v[2:5] offset:64
	ds_read_b128 v[18:21], v250
	ds_read_b128 v[2:5], v250 offset:1152
	s_waitcnt lgkmcnt(0)
	s_waitcnt vmcnt(13)
	v_pk_fma_f32 v[134:135], v[134:135], v[138:139], v[172:173]
	v_pk_fma_f32 v[136:137], v[136:137], v[140:141], v[174:175]
	global_store_dwordx4 v166, v[134:137], s[12:13] sc1
	global_load_dwordx4 v[172:175], v213, s[14:15] nt
	s_waitcnt vmcnt(14)
	v_pk_fma_f32 v[82:83], v[82:83], v[162:163], v[176:177]
	v_pk_fma_f32 v[84:85], v[84:85], v[164:165], v[178:179]
	global_store_dwordx4 v166, v[82:85], s[12:13] offset:512 sc1
	global_load_dwordx4 v[176:179], v213, s[14:15] offset:512 nt
	s_waitcnt vmcnt(15)
	v_pk_fma_f32 v[106:107], v[106:107], v[138:139], v[186:187]
	v_pk_fma_f32 v[108:109], v[108:109], v[140:141], v[188:189]
	global_store_dwordx4 v167, v[106:109], s[12:13] sc1
	global_load_dwordx4 v[186:189], v166, s[16:17] nt
	s_waitcnt vmcnt(16)
	v_pk_fma_f32 v[54:55], v[54:55], v[162:163], v[190:191]
	v_pk_fma_f32 v[56:57], v[56:57], v[164:165], v[192:193]
	global_store_dwordx4 v167, v[54:57], s[12:13] offset:512 sc1
	global_load_dwordx4 v[190:193], v166, s[16:17] offset:512 nt
	s_waitcnt vmcnt(17)
	v_pk_fma_f32 v[130:131], v[130:131], v[138:139], v[194:195]
	v_pk_fma_f32 v[132:133], v[132:133], v[140:141], v[196:197]
	global_store_dwordx4 v180, v[130:133], s[12:13] sc1
	global_load_dwordx4 v[194:197], v167, s[16:17] nt
	s_waitcnt vmcnt(18)
; #define PG8_BAR __builtin_amdgcn_s_barrier()
;     __device__ __forceinline__ void operator()(const f32x4 (&acc)[2][2][4][2], const Unit& u, int wr, int wc, int fr, int fq) const {
;     ...
;                     for (int m = 0; m < 4; ++m) { const size_t off = (size_t)(ai * HALF + wr * 64 + m * 16 + fr) * 1024 + col0 + bj * HALF + n * 16;
;                         const f32x4 s = *(const f32x4*)(src + off); *(f32x4*)(dst + off) = s + gv * acc[ai][bj][m][n]; } }
; template <class Epi, class Sched, bool ALIGN_EPI = false, bool SP2 = false>
; __device__ __forceinline__ void gemm_phase(PG8_LAS unsigned char* lds, const Gemm g, const Sched& S, const Epi& E) {
;     ...
;         cur = nxt; cA = nA; cB = nB; ++ui;
;         if constexpr (ALIGN_EPI) { if (wr == 1) PG8_BAR; }
	v_pk_fma_f32 v[74:75], v[74:75], v[162:163], v[198:199]
	v_pk_fma_f32 v[76:77], v[76:77], v[164:165], v[200:201]
	global_store_dwordx4 v180, v[74:77], s[12:13] offset:512 sc1
	global_load_dwordx4 v[198:201], v167, s[16:17] offset:512 nt
	s_waitcnt vmcnt(19)
	v_pk_fma_f32 v[102:103], v[102:103], v[138:139], v[208:209]
	v_pk_fma_f32 v[104:105], v[104:105], v[140:141], v[210:211]
	global_store_dwordx4 v181, v[102:105], s[12:13] sc1
	global_load_dwordx4 v[208:211], v180, s[16:17] nt
	s_waitcnt vmcnt(20)
	v_pk_fma_f32 v[46:47], v[46:47], v[162:163], v[218:219]
	v_pk_fma_f32 v[48:49], v[48:49], v[164:165], v[220:221]
	global_store_dwordx4 v181, v[46:49], s[12:13] offset:512 sc1
	global_load_dwordx4 v[218:221], v180, s[16:17] offset:512 nt
	s_waitcnt vmcnt(21)
	v_pk_fma_f32 v[126:127], v[126:127], v[138:139], v[226:227]
	v_pk_fma_f32 v[128:129], v[128:129], v[140:141], v[228:229]
	global_store_dwordx4 v202, v[126:129], s[12:13] sc1
	global_load_dwordx4 v[226:229], v181, s[16:17] nt
	s_waitcnt vmcnt(22)
	v_pk_fma_f32 v[66:67], v[66:67], v[162:163], v[230:231]
	v_pk_fma_f32 v[68:69], v[68:69], v[164:165], v[232:233]
	global_store_dwordx4 v202, v[66:69], s[12:13] offset:512 sc1
	global_load_dwordx4 v[230:233], v181, s[16:17] offset:512 nt
	s_waitcnt vmcnt(23)
	v_pk_fma_f32 v[98:99], v[98:99], v[138:139], v[234:235]
	v_pk_fma_f32 v[100:101], v[100:101], v[140:141], v[236:237]
	global_store_dwordx4 v203, v[98:101], s[12:13] sc1
	global_load_dwordx4 v[234:237], v202, s[16:17] nt
	s_waitcnt vmcnt(24)
	v_pk_fma_f32 v[30:31], v[30:31], v[162:163], v[238:239]
	v_pk_fma_f32 v[32:33], v[32:33], v[164:165], v[240:241]
	global_store_dwordx4 v203, v[30:33], s[12:13] offset:512 sc1
	global_load_dwordx4 v[238:241], v202, s[16:17] offset:512 nt
	s_waitcnt vmcnt(25)
	v_pk_fma_f32 v[122:123], v[122:123], v[138:139], v[242:243]
	v_pk_fma_f32 v[124:125], v[124:125], v[140:141], v[244:245]
	global_store_dwordx4 v212, v[122:125], s[12:13] sc1
	global_load_dwordx4 v[242:245], v203, s[16:17] nt
	s_waitcnt vmcnt(26)
	v_pk_fma_f32 v[58:59], v[58:59], v[162:163], v[246:247]
	v_pk_fma_f32 v[60:61], v[60:61], v[164:165], v[248:249]
	global_store_dwordx4 v212, v[58:61], s[12:13] offset:512 sc1
	global_load_dwordx4 v[246:249], v203, s[16:17] offset:512 nt
	s_waitcnt vmcnt(26)
	v_pk_fma_f32 v[90:91], v[90:91], v[138:139], v[172:173]
	v_pk_fma_f32 v[92:93], v[92:93], v[140:141], v[174:175]
	global_store_dwordx4 v213, v[90:93], s[12:13] sc1
	global_load_dwordx4 v[172:175], v212, s[16:17] nt
	s_waitcnt vmcnt(26)
	v_pk_fma_f32 v[22:23], v[22:23], v[162:163], v[176:177]
	v_pk_fma_f32 v[24:25], v[24:25], v[164:165], v[178:179]
	global_store_dwordx4 v213, v[22:25], s[12:13] offset:512 sc1
	global_load_dwordx4 v[176:179], v212, s[16:17] offset:512 nt
	s_waitcnt vmcnt(26)
	v_pk_fma_f32 v[118:119], v[118:119], v[138:139], v[186:187]
	v_pk_fma_f32 v[120:121], v[120:121], v[140:141], v[188:189]
	global_store_dwordx4 v166, v[118:121], s[18:19] sc1
	global_load_dwordx4 v[186:189], v213, s[16:17] nt
	s_waitcnt vmcnt(26)
	v_pk_fma_f32 v[50:51], v[50:51], v[162:163], v[190:191]
	v_pk_fma_f32 v[52:53], v[52:53], v[164:165], v[192:193]
	global_store_dwordx4 v166, v[50:53], s[18:19] offset:512 sc1
	global_load_dwordx4 v[190:193], v213, s[16:17] offset:512 nt
	s_waitcnt vmcnt(26)
	v_pk_fma_f32 v[86:87], v[86:87], v[138:139], v[194:195]
	v_pk_fma_f32 v[88:89], v[88:89], v[140:141], v[196:197]
	global_store_dwordx4 v167, v[86:89], s[18:19] sc1
	s_waitcnt vmcnt(25)
	v_pk_fma_f32 v[14:15], v[14:15], v[162:163], v[198:199]
	v_pk_fma_f32 v[16:17], v[16:17], v[164:165], v[200:201]
	global_store_dwordx4 v167, v[14:17], s[18:19] offset:512 sc1
	s_waitcnt vmcnt(24)
	v_pk_fma_f32 v[114:115], v[114:115], v[138:139], v[208:209]
	v_pk_fma_f32 v[116:117], v[116:117], v[140:141], v[210:211]
	global_store_dwordx4 v180, v[114:117], s[18:19] sc1
	s_waitcnt vmcnt(23)
	v_pk_fma_f32 v[42:43], v[42:43], v[162:163], v[218:219]
	v_pk_fma_f32 v[44:45], v[44:45], v[164:165], v[220:221]
	global_store_dwordx4 v180, v[42:45], s[18:19] offset:512 sc1
	s_waitcnt vmcnt(22)
	v_pk_fma_f32 v[78:79], v[78:79], v[138:139], v[226:227]
	v_pk_fma_f32 v[80:81], v[80:81], v[140:141], v[228:229]
	global_store_dwordx4 v181, v[78:81], s[18:19] sc1
	s_waitcnt vmcnt(21)
	v_pk_fma_f32 v[10:11], v[10:11], v[162:163], v[230:231]
	v_pk_fma_f32 v[12:13], v[12:13], v[164:165], v[232:233]
	global_store_dwordx4 v181, v[10:13], s[18:19] offset:512 sc1
	s_waitcnt vmcnt(20)
	v_pk_fma_f32 v[110:111], v[110:111], v[138:139], v[234:235]
	v_pk_fma_f32 v[112:113], v[112:113], v[140:141], v[236:237]
	global_store_dwordx4 v202, v[110:113], s[18:19] sc1
	s_waitcnt vmcnt(19)
	v_pk_fma_f32 v[26:27], v[26:27], v[162:163], v[238:239]
	v_pk_fma_f32 v[28:29], v[28:29], v[164:165], v[240:241]
	global_store_dwordx4 v202, v[26:29], s[18:19] offset:512 sc1
	s_waitcnt vmcnt(18)
	v_pk_fma_f32 v[70:71], v[70:71], v[138:139], v[242:243]
	v_pk_fma_f32 v[72:73], v[72:73], v[140:141], v[244:245]
	global_store_dwordx4 v203, v[70:73], s[18:19] sc1
	s_waitcnt vmcnt(17)
	v_pk_fma_f32 v[6:7], v[6:7], v[162:163], v[246:247]
	v_pk_fma_f32 v[8:9], v[8:9], v[164:165], v[248:249]
	global_store_dwordx4 v203, v[6:9], s[18:19] offset:512 sc1
	s_waitcnt vmcnt(16)
	v_pk_fma_f32 v[94:95], v[94:95], v[138:139], v[172:173]
	v_pk_fma_f32 v[96:97], v[96:97], v[140:141], v[174:175]
	global_store_dwordx4 v212, v[94:97], s[18:19] sc1
	s_waitcnt vmcnt(15)
	v_pk_fma_f32 v[18:19], v[18:19], v[162:163], v[176:177]
	v_pk_fma_f32 v[20:21], v[20:21], v[164:165], v[178:179]
	global_store_dwordx4 v212, v[18:21], s[18:19] offset:512 sc1
	s_waitcnt vmcnt(14)
	v_pk_fma_f32 v[62:63], v[62:63], v[138:139], v[186:187]
	v_pk_fma_f32 v[64:65], v[64:65], v[140:141], v[188:189]
	global_store_dwordx4 v213, v[62:65], s[18:19] sc1
	s_waitcnt vmcnt(13)
	v_pk_fma_f32 v[2:3], v[2:3], v[162:163], v[190:191]
	v_pk_fma_f32 v[4:5], v[4:5], v[164:165], v[192:193]
	global_store_dwordx4 v213, v[2:5], s[18:19] offset:512 sc1
	s_mov_b64 s[10:11], -1
	s_and_b64 vcc, exec, s[4:5]
	s_cbranch_vccnz .LBB0_978
	s_andn2_b64 vcc, exec, s[2:3]
	s_cbranch_vccnz .LBB0_977
	s_barrier
	s_branch .LBB0_977
